# stack6 + EpiResidNorm: wave 0's row-counter spin moved right after the counter add (before its h stores / modulation loads), 4 instances
# baseline (speedup 1.0000x reference)
;     __device__ __forceinline__ void operator()(f32x4 (&acc)[2][2][4][2], const Unit& u, int wr, int wc, int fr_, int fq_) const {
;     ...
;         if (wid == 0) { if (lane == 0) { unsigned sp = 0u; while (__hip_atomic_load(cnt + 16 * u.pm, __ATOMIC_RELAXED, __HIP_MEMORY_SCOPE_AGENT) < 64u) { __builtin_amdgcn_s_sleep(1); if (++sp > (1u << 17)) break; } } }
.LBB0_331:
	s_or_b64 exec, exec, s[0:1]
	v_or_b32_e32 v188, s94, v201
	v_cmp_eq_u32_e32 vcc, 0, v188
	s_and_saveexec_b64 s[0:1], vcc
	s_cbranch_execz .LBB0_338
	s_lshl_b32 s44, s28, 4
	s_ashr_i32 s45, s44, 31
	s_lshl_b64 s[44:45], s[44:45], 2
	s_add_u32 s44, s73, s44
	s_addc_u32 s45, s81, s45
	s_mov_b32 s29, 0x20001
	s_branch .LBB0_334

; __device__ __forceinline__ u32x4 pack8h(const f32x4 v0, const f32x4 v1) { u32x4 w; w.x = pk_h2(v0[0], v0[1]); w.y = pk_h2(v0[2], v0[3]); w.z = pk_h2(v1[0], v1[1]); w.w = pk_h2(v1[2], v1[3]); return w; }
;     __device__ __forceinline__ void operator()(f32x4 (&acc)[2][2][4][2], const Unit& u, int wr, int wc, int fr_, int fq_) const {
;     ...
;         if (!FINAL) { bf16_t* out = (lat ? out_lat : out_ctx) + roff;
; #pragma unroll
;             for (int ai = 0; ai < 2; ++ai)
; #pragma unroll
;                 for (int m = 0; m < 4; ++m)
; #pragma unroll
;                     for (int bj = 0; bj < 2; ++bj) *(u32x4*)(out + (size_t)(ai * HALF + m * 16) * DM + bj * HALF) = pack8h(acc[ai][bj][m][0], acc[ai][bj][m][1]); }
;         f32x4 av[2][2], sv[2][2];
; #pragma unroll
;         for (int bj = 0; bj < 2; ++bj)
; #pragma unroll
;             for (int n = 0; n < 2; ++n) { const int col = col0 + bj * HALF + 4 * n; const f32x4 g = *(const f32x4*)(gain + col);
;                 if (FINAL) { av[bj][n] = g; sv[bj][n] = (f32x4){0.f, 0.f, 0.f, 0.f}; }
;                 else { const float* mp = nmod + (size_t)rb * NMODC; av[bj][n] = g * (*(const f32x4*)(mp + isc * DM + col) + 1.0f); sv[bj][n] = *(const f32x4*)(mp + ish * DM + col); } }
;         if (wid == 0) { if (lane == 0) { unsigned sp = 0u; while (__hip_atomic_load(cnt + 16 * u.pm, __ATOMIC_RELAXED, __HIP_MEMORY_SCOPE_AGENT) < 64u) { __builtin_amdgcn_s_sleep(1); if (++sp > (1u << 17)) break; } } }
;         asm volatile("s_waitcnt lgkmcnt(0)" ::: "memory"); __builtin_amdgcn_s_barrier(); asm volatile("" ::: "memory");
;         if (lane < 32) { const float* slot = xbuf + ((size_t)u.pm * BM + row) * 8; float t8[8];
; #pragma unroll
;             for (int t = 0; t < 8; ++t) t8[t] = __hip_atomic_load(slot + t, __ATOMIC_RELAXED, __HIP_MEMORY_SCOPE_AGENT);
;             const float tot = ((t8[0] + t8[1]) + (t8[2] + t8[3])) + ((t8[4] + t8[5]) + (t8[6] + t8[7]));
;             S[row] = __builtin_amdgcn_rsqf(tot * (1.0f / DM) + 1e-6f); }
.LBB0_334:
	global_load_dword v188, v187, s[44:45] sc1
	s_mov_b64 s[40:41], -1
	s_waitcnt vmcnt(0)
	v_cmp_lt_u32_e32 vcc, 63, v188
	s_cbranch_vccnz .LBB0_333
	s_sleep 1
	global_load_dword v188, v187, s[44:45] sc1
	s_waitcnt vmcnt(0)
	v_cmp_gt_u32_e32 vcc, 64, v188
	s_cbranch_vccz .LBB0_333
	s_sleep 1
	global_load_dword v188, v187, s[44:45] sc1
	s_waitcnt vmcnt(0)
	v_cmp_gt_u32_e32 vcc, 64, v188
	s_cbranch_vccz .LBB0_333
	s_add_i32 s29, s29, -3
	s_cmp_eq_u32 s29, 0
	s_cselect_b64 s[40:41], -1, 0
	s_sleep 1
	s_branch .LBB0_333
.LBB0_338:
	s_or_b64 exec, exec, s[0:1]
	s_and_b64 s[0:1], s[36:37], exec
	s_cselect_b32 s0, s11, s13
	s_cselect_b32 s1, s10, s12
	v_mov_b32_e32 v130, s1
	v_mov_b32_e32 v131, s0
	v_lshl_add_u64 v[134:135], v[148:149], 1, v[130:131]
	v_cvt_pk_f16_f32 v130, v30, v31
	v_cvt_pk_f16_f32 v131, v32, v33
	v_cvt_pk_f16_f32 v132, v22, v23
	v_cvt_pk_f16_f32 v133, v24, v25
	global_store_dwordx4 v[134:135], v[130:133], off
	v_add_co_u32_e32 v136, vcc, s75, v134
	s_nop 0
	v_cvt_pk_f16_f32 v130, v26, v27
	v_cvt_pk_f16_f32 v131, v28, v29
	v_cvt_pk_f16_f32 v132, v18, v19
	v_cvt_pk_f16_f32 v133, v20, v21
	global_store_dwordx4 v[134:135], v[130:133], off offset:256
	v_addc_co_u32_e32 v137, vcc, 0, v135, vcc
	s_nop 0
	v_cvt_pk_f16_f32 v130, v10, v11
	v_cvt_pk_f16_f32 v131, v12, v13
	v_cvt_pk_f16_f32 v132, v6, v7
	v_cvt_pk_f16_f32 v133, v8, v9
	global_store_dwordx4 v[136:137], v[130:133], off
	s_mov_b32 s0, 0x90000
	v_cvt_pk_f16_f32 v130, v42, v43
	v_cvt_pk_f16_f32 v131, v44, v45
	v_cvt_pk_f16_f32 v132, v46, v47
	v_cvt_pk_f16_f32 v133, v48, v49
	global_store_dwordx4 v[136:137], v[130:133], off offset:256
	v_add_co_u32_e32 v136, vcc, s46, v134
	s_nop 0
	v_cvt_pk_f16_f32 v130, v50, v51
	v_cvt_pk_f16_f32 v131, v52, v53
	v_cvt_pk_f16_f32 v132, v54, v55
	v_cvt_pk_f16_f32 v133, v56, v57
	v_addc_co_u32_e32 v137, vcc, 0, v135, vcc
	global_store_dwordx4 v[136:137], v[130:133], off
	s_nop 1
	v_cvt_pk_f16_f32 v130, v66, v67
	v_cvt_pk_f16_f32 v131, v68, v69
	v_cvt_pk_f16_f32 v132, v70, v71
	v_cvt_pk_f16_f32 v133, v72, v73
	global_store_dwordx4 v[136:137], v[130:133], off offset:256
	v_add_co_u32_e32 v136, vcc, s80, v134
	s_nop 0
	v_cvt_pk_f16_f32 v130, v74, v75
	v_cvt_pk_f16_f32 v131, v76, v77
	v_cvt_pk_f16_f32 v132, v78, v79
	v_cvt_pk_f16_f32 v133, v80, v81
	v_addc_co_u32_e32 v137, vcc, 0, v135, vcc
	global_store_dwordx4 v[136:137], v[130:133], off
	s_nop 1
	v_cvt_pk_f16_f32 v130, v82, v83
	v_cvt_pk_f16_f32 v131, v84, v85
	v_cvt_pk_f16_f32 v132, v86, v87
	v_cvt_pk_f16_f32 v133, v88, v89
	global_store_dwordx4 v[136:137], v[130:133], off offset:256
	v_add_co_u32_e32 v136, vcc, s52, v134
	s_nop 0
	v_cvt_pk_f16_f32 v130, v106, v107
	v_cvt_pk_f16_f32 v131, v108, v109
	v_cvt_pk_f16_f32 v132, v110, v111
	v_cvt_pk_f16_f32 v133, v112, v113
	v_addc_co_u32_e32 v137, vcc, 0, v135, vcc
	global_store_dwordx4 v[136:137], v[130:133], off
	s_nop 1
	v_cvt_pk_f16_f32 v130, v114, v115
	v_cvt_pk_f16_f32 v131, v116, v117
	v_cvt_pk_f16_f32 v132, v118, v119
	v_cvt_pk_f16_f32 v133, v120, v121
	global_store_dwordx4 v[136:137], v[130:133], off offset:256
	v_add_co_u32_e32 v136, vcc, s0, v134
	s_nop 0
	v_cvt_pk_f16_f32 v130, v122, v123
	v_cvt_pk_f16_f32 v131, v124, v125
	v_cvt_pk_f16_f32 v132, v126, v127
	v_cvt_pk_f16_f32 v133, v128, v129
	v_addc_co_u32_e32 v137, vcc, 0, v135, vcc
	global_store_dwordx4 v[136:137], v[130:133], off
	s_mov_b32 s0, 0xa0000
	s_nop 0
	v_cvt_pk_f16_f32 v130, v102, v103
	v_cvt_pk_f16_f32 v131, v104, v105
	v_cvt_pk_f16_f32 v132, v98, v99
	v_cvt_pk_f16_f32 v133, v100, v101
	global_store_dwordx4 v[136:137], v[130:133], off offset:256
	v_add_co_u32_e32 v136, vcc, s0, v134
	s_nop 0
	v_cvt_pk_f16_f32 v130, v94, v95
	v_cvt_pk_f16_f32 v131, v96, v97
	v_cvt_pk_f16_f32 v132, v90, v91
	v_cvt_pk_f16_f32 v133, v92, v93
	v_addc_co_u32_e32 v137, vcc, 0, v135, vcc
	s_mov_b32 s0, 0xb0000
	global_store_dwordx4 v[136:137], v[130:133], off
	v_add_co_u32_e32 v134, vcc, s0, v134
	s_nop 0
	v_cvt_pk_f16_f32 v130, v62, v63
	v_cvt_pk_f16_f32 v131, v64, v65
	v_cvt_pk_f16_f32 v132, v58, v59
	v_cvt_pk_f16_f32 v133, v60, v61
	global_store_dwordx4 v[136:137], v[130:133], off offset:256
	v_addc_co_u32_e32 v135, vcc, 0, v135, vcc
	s_nop 0
	v_cvt_pk_f16_f32 v130, v38, v39
	v_cvt_pk_f16_f32 v131, v40, v41
	v_cvt_pk_f16_f32 v132, v34, v35
	v_cvt_pk_f16_f32 v133, v36, v37
	global_store_dwordx4 v[134:135], v[130:133], off
	s_mov_b64 s[0:1], 0x6000
	s_nop 0
	v_cvt_pk_f16_f32 v130, v14, v15
	v_cvt_pk_f16_f32 v131, v16, v17
	v_cvt_pk_f16_f32 v132, v2, v3
	v_cvt_pk_f16_f32 v133, v4, v5
	global_store_dwordx4 v[134:135], v[130:133], off offset:256
	s_nop 1
	v_lshlrev_b64 v[130:131], 2, v[146:147]
	v_lshl_add_u64 v[132:133], s[14:15], 0, v[130:131]
	v_lshl_add_u64 v[130:131], s[34:35], 0, v[130:131]
	v_add_co_u32_e32 v136, vcc, s69, v130
	v_lshl_add_u64 v[134:135], v[130:131], 0, s[90:91]
	s_nop 0
	v_addc_co_u32_e32 v137, vcc, 0, v131, vcc
	v_lshl_add_u64 v[208:209], v[130:131], 0, s[0:1]
	v_add_co_u32_e32 v130, vcc, 0x6000, v130
	global_load_dwordx4 v[150:153], v[132:133], off offset:16
	global_load_dwordx4 v[146:149], v[132:133], off
	v_addc_co_u32_e32 v131, vcc, 0, v131, vcc
	global_load_dwordx4 v[166:169], v[132:133], off offset:528
	global_load_dwordx4 v[162:165], v[132:133], off offset:512
	global_load_dwordx4 v[154:157], v[136:137], off
	global_load_dwordx4 v[174:177], v[134:135], off offset:528
	global_load_dwordx4 v[158:161], v[134:135], off offset:16
	global_load_dwordx4 v[170:173], v[134:135], off offset:512
	global_load_dwordx4 v[142:145], v[130:131], off
	s_nop 0
	global_load_dwordx4 v[130:133], v[208:209], off offset:528
	global_load_dwordx4 v[138:141], v[208:209], off offset:16
	global_load_dwordx4 v[134:137], v[208:209], off offset:512
	s_waitcnt lgkmcnt(0)
	s_barrier
	s_ashr_i32 s29, s28, 31
	s_and_saveexec_b64 s[0:1], s[8:9]
	s_cbranch_execz .LBB0_340
	s_lshl_b64 s[8:9], s[28:29], 13
	s_add_u32 s8, s68, s8
	s_addc_u32 s9, s72, s9
	v_lshlrev_b64 v[208:209], 5, v[202:203]
	v_lshl_add_u64 v[208:209], s[8:9], 0, v[208:209]
	global_load_dword v210, v[208:209], off sc1
	global_load_dword v212, v[208:209], off offset:4 sc1
	global_load_dword v214, v[208:209], off offset:8 sc1
	global_load_dword v216, v[208:209], off offset:12 sc1
	global_load_dword v211, v[208:209], off offset:16 sc1
	global_load_dword v213, v[208:209], off offset:20 sc1
	global_load_dword v215, v[208:209], off offset:24 sc1
	global_load_dword v217, v[208:209], off offset:28 sc1
	v_lshl_add_u32 v189, v202, 2, 0
	v_add_u32_e32 v189, 0x21540, v189
	s_waitcnt vmcnt(2)
	v_pk_add_f32 v[208:209], v[210:211], v[212:213]
	s_waitcnt vmcnt(0)
	v_pk_add_f32 v[210:211], v[214:215], v[216:217]
	s_nop 0
	v_pk_add_f32 v[208:209], v[208:209], v[210:211]
	s_nop 0
	v_add_f32_e32 v188, v208, v209
	v_fmamk_f32 v188, v188, 0x3a000000, v1
	v_rsq_f32_e32 v188, v188
	ds_write_b32 v189, v188

;     __device__ __forceinline__ void operator()(f32x4 (&acc)[2][2][4][2], const Unit& u, int wr, int wc, int fr_, int fq_) const {
;     ...
;         if (wid == 0) { if (lane == 0) { unsigned sp = 0u; while (__hip_atomic_load(cnt + 16 * u.pm, __ATOMIC_RELAXED, __HIP_MEMORY_SCOPE_AGENT) < 64u) { __builtin_amdgcn_s_sleep(1); if (++sp > (1u << 17)) break; } } }
.LBB0_394:
	s_or_b64 exec, exec, s[0:1]
	v_or_b32_e32 v188, s53, v201
	v_cmp_eq_u32_e32 vcc, 0, v188
	s_and_saveexec_b64 s[0:1], vcc
	s_cbranch_execz .LBB0_401
	s_lshl_b32 s44, s28, 4
	s_ashr_i32 s45, s44, 31
	s_lshl_b64 s[44:45], s[44:45], 2
	s_add_u32 s44, s4, s44
	s_addc_u32 s45, s5, s45
	s_mov_b32 s29, 0x20001
	s_branch .LBB0_397

; __device__ __forceinline__ u32x4 pack8h(const f32x4 v0, const f32x4 v1) { u32x4 w; w.x = pk_h2(v0[0], v0[1]); w.y = pk_h2(v0[2], v0[3]); w.z = pk_h2(v1[0], v1[1]); w.w = pk_h2(v1[2], v1[3]); return w; }
;     __device__ __forceinline__ void operator()(f32x4 (&acc)[2][2][4][2], const Unit& u, int wr, int wc, int fr_, int fq_) const {
;     ...
;         if (!FINAL) { bf16_t* out = (lat ? out_lat : out_ctx) + roff;
; #pragma unroll
;             for (int ai = 0; ai < 2; ++ai)
; #pragma unroll
;                 for (int m = 0; m < 4; ++m)
; #pragma unroll
;                     for (int bj = 0; bj < 2; ++bj) *(u32x4*)(out + (size_t)(ai * HALF + m * 16) * DM + bj * HALF) = pack8h(acc[ai][bj][m][0], acc[ai][bj][m][1]); }
;         f32x4 av[2][2], sv[2][2];
; #pragma unroll
;         for (int bj = 0; bj < 2; ++bj)
; #pragma unroll
;             for (int n = 0; n < 2; ++n) { const int col = col0 + bj * HALF + 4 * n; const f32x4 g = *(const f32x4*)(gain + col);
;                 if (FINAL) { av[bj][n] = g; sv[bj][n] = (f32x4){0.f, 0.f, 0.f, 0.f}; }
;                 else { const float* mp = nmod + (size_t)rb * NMODC; av[bj][n] = g * (*(const f32x4*)(mp + isc * DM + col) + 1.0f); sv[bj][n] = *(const f32x4*)(mp + ish * DM + col); } }
;         if (wid == 0) { if (lane == 0) { unsigned sp = 0u; while (__hip_atomic_load(cnt + 16 * u.pm, __ATOMIC_RELAXED, __HIP_MEMORY_SCOPE_AGENT) < 64u) { __builtin_amdgcn_s_sleep(1); if (++sp > (1u << 17)) break; } } }
;         asm volatile("s_waitcnt lgkmcnt(0)" ::: "memory"); __builtin_amdgcn_s_barrier(); asm volatile("" ::: "memory");
;         if (lane < 32) { const float* slot = xbuf + ((size_t)u.pm * BM + row) * 8; float t8[8];
; #pragma unroll
;             for (int t = 0; t < 8; ++t) t8[t] = __hip_atomic_load(slot + t, __ATOMIC_RELAXED, __HIP_MEMORY_SCOPE_AGENT);
;             const float tot = ((t8[0] + t8[1]) + (t8[2] + t8[3])) + ((t8[4] + t8[5]) + (t8[6] + t8[7]));
;             S[row] = __builtin_amdgcn_rsqf(tot * (1.0f / DM) + 1e-6f); }
.LBB0_401:
	s_or_b64 exec, exec, s[0:1]
	s_and_b64 s[0:1], s[36:37], exec
	s_cselect_b32 s0, s95, s97
	s_cselect_b32 s1, s94, s96
	v_mov_b32_e32 v98, s1
	v_mov_b32_e32 v99, s0
	v_lshl_add_u64 v[102:103], v[140:141], 1, v[98:99]
	v_cvt_pk_f16_f32 v98, v30, v31
	v_cvt_pk_f16_f32 v99, v32, v33
	v_cvt_pk_f16_f32 v100, v26, v27
	v_cvt_pk_f16_f32 v101, v28, v29
	global_store_dwordx4 v[102:103], v[98:101], off
	v_add_co_u32_e32 v104, vcc, s80, v102
	s_nop 0
	v_cvt_pk_f16_f32 v98, v22, v23
	v_cvt_pk_f16_f32 v99, v24, v25
	v_cvt_pk_f16_f32 v100, v18, v19
	v_cvt_pk_f16_f32 v101, v20, v21
	global_store_dwordx4 v[102:103], v[98:101], off offset:256
	v_addc_co_u32_e32 v105, vcc, 0, v103, vcc
	s_nop 0
	v_cvt_pk_f16_f32 v98, v14, v15
	v_cvt_pk_f16_f32 v99, v16, v17
	v_cvt_pk_f16_f32 v100, v10, v11
	v_cvt_pk_f16_f32 v101, v12, v13
	global_store_dwordx4 v[104:105], v[98:101], off
	s_mov_b32 s0, 0x90000
	v_cvt_pk_f16_f32 v98, v6, v7
	v_cvt_pk_f16_f32 v99, v8, v9
	v_cvt_pk_f16_f32 v100, v2, v3
	v_cvt_pk_f16_f32 v101, v4, v5
	global_store_dwordx4 v[104:105], v[98:101], off offset:256
	v_add_co_u32_e32 v104, vcc, s46, v102
	s_nop 0
	v_cvt_pk_f16_f32 v98, v62, v63
	v_cvt_pk_f16_f32 v99, v64, v65
	v_cvt_pk_f16_f32 v100, v58, v59
	v_cvt_pk_f16_f32 v101, v60, v61
	v_addc_co_u32_e32 v105, vcc, 0, v103, vcc
	global_store_dwordx4 v[104:105], v[98:101], off
	s_nop 1
	v_cvt_pk_f16_f32 v98, v54, v55
	v_cvt_pk_f16_f32 v99, v56, v57
	v_cvt_pk_f16_f32 v100, v50, v51
	v_cvt_pk_f16_f32 v101, v52, v53
	global_store_dwordx4 v[104:105], v[98:101], off offset:256
	v_add_co_u32_e32 v104, vcc, s82, v102
	s_nop 0
	v_cvt_pk_f16_f32 v98, v46, v47
	v_cvt_pk_f16_f32 v99, v48, v49
	v_cvt_pk_f16_f32 v100, v42, v43
	v_cvt_pk_f16_f32 v101, v44, v45
	v_addc_co_u32_e32 v105, vcc, 0, v103, vcc
	global_store_dwordx4 v[104:105], v[98:101], off
	s_nop 1
	v_cvt_pk_f16_f32 v98, v38, v39
	v_cvt_pk_f16_f32 v99, v40, v41
	v_cvt_pk_f16_f32 v100, v34, v35
	v_cvt_pk_f16_f32 v101, v36, v37
	global_store_dwordx4 v[104:105], v[98:101], off offset:256
	v_add_co_u32_e32 v104, vcc, s75, v102
	s_nop 0
	v_cvt_pk_f16_f32 v98, v126, v127
	v_cvt_pk_f16_f32 v99, v128, v129
	v_cvt_pk_f16_f32 v100, v122, v123
	v_cvt_pk_f16_f32 v101, v124, v125
	v_addc_co_u32_e32 v105, vcc, 0, v103, vcc
	global_store_dwordx4 v[104:105], v[98:101], off
	s_nop 1
	v_cvt_pk_f16_f32 v98, v118, v119
	v_cvt_pk_f16_f32 v99, v120, v121
	v_cvt_pk_f16_f32 v100, v114, v115
	v_cvt_pk_f16_f32 v101, v116, v117
	global_store_dwordx4 v[104:105], v[98:101], off offset:256
	v_add_co_u32_e32 v104, vcc, s0, v102
	s_nop 0
	v_cvt_pk_f16_f32 v98, v94, v95
	v_cvt_pk_f16_f32 v99, v96, v97
	v_cvt_pk_f16_f32 v100, v90, v91
	v_cvt_pk_f16_f32 v101, v92, v93
	v_addc_co_u32_e32 v105, vcc, 0, v103, vcc
	global_store_dwordx4 v[104:105], v[98:101], off
	s_mov_b32 s0, 0xa0000
	s_nop 0
	v_cvt_pk_f16_f32 v98, v74, v75
	v_cvt_pk_f16_f32 v99, v76, v77
	v_cvt_pk_f16_f32 v100, v70, v71
	v_cvt_pk_f16_f32 v101, v72, v73
	global_store_dwordx4 v[104:105], v[98:101], off offset:256
	v_add_co_u32_e32 v104, vcc, s0, v102
	s_nop 0
	v_cvt_pk_f16_f32 v98, v134, v135
	v_cvt_pk_f16_f32 v99, v136, v137
	v_cvt_pk_f16_f32 v100, v130, v131
	v_cvt_pk_f16_f32 v101, v132, v133
	v_addc_co_u32_e32 v105, vcc, 0, v103, vcc
	s_mov_b32 s0, 0xb0000
	global_store_dwordx4 v[104:105], v[98:101], off
	v_add_co_u32_e32 v102, vcc, s0, v102
	s_nop 0
	v_cvt_pk_f16_f32 v98, v110, v111
	v_cvt_pk_f16_f32 v99, v112, v113
	v_cvt_pk_f16_f32 v100, v106, v107
	v_cvt_pk_f16_f32 v101, v108, v109
	global_store_dwordx4 v[104:105], v[98:101], off offset:256
	v_addc_co_u32_e32 v103, vcc, 0, v103, vcc
	s_nop 0
	v_cvt_pk_f16_f32 v98, v86, v87
	v_cvt_pk_f16_f32 v99, v88, v89
	v_cvt_pk_f16_f32 v100, v82, v83
	v_cvt_pk_f16_f32 v101, v84, v85
	global_store_dwordx4 v[102:103], v[98:101], off
	s_mov_b64 s[0:1], 0x6000
	s_nop 0
	v_cvt_pk_f16_f32 v98, v78, v79
	v_cvt_pk_f16_f32 v99, v80, v81
	v_cvt_pk_f16_f32 v100, v66, v67
	v_cvt_pk_f16_f32 v101, v68, v69
	global_store_dwordx4 v[102:103], v[98:101], off offset:256
	s_nop 1
	v_lshlrev_b64 v[98:99], 2, v[138:139]
	v_lshl_add_u64 v[100:101], s[12:13], 0, v[98:99]
	v_lshl_add_u64 v[98:99], s[34:35], 0, v[98:99]
	v_add_co_u32_e32 v104, vcc, s69, v98
	v_lshl_add_u64 v[102:103], v[98:99], 0, s[90:91]
	s_nop 0
	v_addc_co_u32_e32 v105, vcc, 0, v99, vcc
	v_lshl_add_u64 v[208:209], v[98:99], 0, s[0:1]
	v_add_co_u32_e32 v98, vcc, 0x6000, v98
	global_load_dwordx4 v[150:153], v[100:101], off offset:16
	global_load_dwordx4 v[146:149], v[100:101], off
	v_addc_co_u32_e32 v99, vcc, 0, v99, vcc
	global_load_dwordx4 v[166:169], v[100:101], off offset:528
	global_load_dwordx4 v[162:165], v[100:101], off offset:512
	global_load_dwordx4 v[154:157], v[104:105], off
	global_load_dwordx4 v[174:177], v[102:103], off offset:528
	global_load_dwordx4 v[158:161], v[102:103], off offset:16
	global_load_dwordx4 v[170:173], v[102:103], off offset:512
	global_load_dwordx4 v[142:145], v[98:99], off
	s_nop 0
	global_load_dwordx4 v[98:101], v[208:209], off offset:528
	global_load_dwordx4 v[138:141], v[208:209], off offset:16
	global_load_dwordx4 v[102:105], v[208:209], off offset:512
	s_waitcnt lgkmcnt(0)
	s_barrier
	s_ashr_i32 s29, s28, 31
	s_and_saveexec_b64 s[0:1], s[8:9]
	s_cbranch_execz .LBB0_403
	s_lshl_b64 s[8:9], s[28:29], 13
	s_add_u32 s8, s14, s8
	s_addc_u32 s9, s15, s9
	v_lshlrev_b64 v[208:209], 5, v[202:203]
	v_lshl_add_u64 v[208:209], s[8:9], 0, v[208:209]
	global_load_dword v210, v[208:209], off sc1
	global_load_dword v212, v[208:209], off offset:4 sc1
	global_load_dword v214, v[208:209], off offset:8 sc1
	global_load_dword v216, v[208:209], off offset:12 sc1
	global_load_dword v211, v[208:209], off offset:16 sc1
	global_load_dword v213, v[208:209], off offset:20 sc1
	global_load_dword v215, v[208:209], off offset:24 sc1
	global_load_dword v217, v[208:209], off offset:28 sc1
	v_lshl_add_u32 v189, v202, 2, 0
	v_add_u32_e32 v189, 0x21540, v189
	s_waitcnt vmcnt(2)
	v_pk_add_f32 v[208:209], v[210:211], v[212:213]
	s_waitcnt vmcnt(0)
	v_pk_add_f32 v[210:211], v[214:215], v[216:217]
	s_nop 0
	v_pk_add_f32 v[208:209], v[208:209], v[210:211]
	s_nop 0
	v_add_f32_e32 v188, v208, v209
	v_fmamk_f32 v188, v188, 0x3a000000, v1
	v_rsq_f32_e32 v188, v188
	ds_write_b32 v189, v188

;     __device__ __forceinline__ void operator()(f32x4 (&acc)[2][2][4][2], const Unit& u, int wr, int wc, int fr_, int fq_) const {
;     ...
;         if (wid == 0) { if (lane == 0) { unsigned sp = 0u; while (__hip_atomic_load(cnt + 16 * u.pm, __ATOMIC_RELAXED, __HIP_MEMORY_SCOPE_AGENT) < 64u) { __builtin_amdgcn_s_sleep(1); if (++sp > (1u << 17)) break; } } }
.LBB0_1265:
	s_or_b64 exec, exec, s[60:61]
	v_or_b32_e32 v188, s90, v201
	v_cmp_eq_u32_e32 vcc, 0, v188
	s_and_saveexec_b64 s[100:101], vcc
	s_cbranch_execz .LBB0_1272
	s_lshl_b32 s92, s36, 4
	s_ashr_i32 s93, s92, 31
	s_lshl_b64 s[92:93], s[92:93], 2
	s_add_u32 s92, s94, s92
	s_addc_u32 s93, s95, s93
	s_mov_b32 s25, 0x20001
	s_branch .LBB0_1268

; __device__ __forceinline__ u32x4 pack8h(const f32x4 v0, const f32x4 v1) { u32x4 w; w.x = pk_h2(v0[0], v0[1]); w.y = pk_h2(v0[2], v0[3]); w.z = pk_h2(v1[0], v1[1]); w.w = pk_h2(v1[2], v1[3]); return w; }
;     __device__ __forceinline__ void operator()(f32x4 (&acc)[2][2][4][2], const Unit& u, int wr, int wc, int fr_, int fq_) const {
;     ...
;         if (!FINAL) { bf16_t* out = (lat ? out_lat : out_ctx) + roff;
; #pragma unroll
;             for (int ai = 0; ai < 2; ++ai)
; #pragma unroll
;                 for (int m = 0; m < 4; ++m)
; #pragma unroll
;                     for (int bj = 0; bj < 2; ++bj) *(u32x4*)(out + (size_t)(ai * HALF + m * 16) * DM + bj * HALF) = pack8h(acc[ai][bj][m][0], acc[ai][bj][m][1]); }
;         f32x4 av[2][2], sv[2][2];
; #pragma unroll
;         for (int bj = 0; bj < 2; ++bj)
; #pragma unroll
;             for (int n = 0; n < 2; ++n) { const int col = col0 + bj * HALF + 4 * n; const f32x4 g = *(const f32x4*)(gain + col);
;                 if (FINAL) { av[bj][n] = g; sv[bj][n] = (f32x4){0.f, 0.f, 0.f, 0.f}; }
;                 else { const float* mp = nmod + (size_t)rb * NMODC; av[bj][n] = g * (*(const f32x4*)(mp + isc * DM + col) + 1.0f); sv[bj][n] = *(const f32x4*)(mp + ish * DM + col); } }
;         if (wid == 0) { if (lane == 0) { unsigned sp = 0u; while (__hip_atomic_load(cnt + 16 * u.pm, __ATOMIC_RELAXED, __HIP_MEMORY_SCOPE_AGENT) < 64u) { __builtin_amdgcn_s_sleep(1); if (++sp > (1u << 17)) break; } } }
;         asm volatile("s_waitcnt lgkmcnt(0)" ::: "memory"); __builtin_amdgcn_s_barrier(); asm volatile("" ::: "memory");
;         if (lane < 32) { const float* slot = xbuf + ((size_t)u.pm * BM + row) * 8; float t8[8];
; #pragma unroll
;             for (int t = 0; t < 8; ++t) t8[t] = __hip_atomic_load(slot + t, __ATOMIC_RELAXED, __HIP_MEMORY_SCOPE_AGENT);
;             const float tot = ((t8[0] + t8[1]) + (t8[2] + t8[3])) + ((t8[4] + t8[5]) + (t8[6] + t8[7]));
;             S[row] = __builtin_amdgcn_rsqf(tot * (1.0f / DM) + 1e-6f); }
.LBB0_1268:
	global_load_dword v188, v187, s[92:93] sc1
	s_mov_b64 s[60:61], -1
	s_waitcnt vmcnt(0)
	v_cmp_lt_u32_e32 vcc, 63, v188
	s_cbranch_vccnz .LBB0_1267
	s_sleep 1
	global_load_dword v188, v187, s[92:93] sc1
	s_waitcnt vmcnt(0)
	v_cmp_gt_u32_e32 vcc, 64, v188
	s_cbranch_vccz .LBB0_1267
	s_sleep 1
	global_load_dword v188, v187, s[92:93] sc1
	s_waitcnt vmcnt(0)
	v_cmp_gt_u32_e32 vcc, 64, v188
	s_cbranch_vccz .LBB0_1267
	s_add_i32 s25, s25, -3
	s_cmp_eq_u32 s25, 0
	s_cselect_b64 s[60:61], -1, 0
	s_sleep 1
	s_branch .LBB0_1267
.LBB0_1272:
	s_or_b64 exec, exec, s[100:101]
	s_and_b64 s[40:41], s[40:41], exec
	s_cselect_b32 s25, s73, s13
	s_cselect_b32 s27, s81, s12
	v_mov_b32_e32 v130, s27
	v_mov_b32_e32 v131, s25
	v_lshl_add_u64 v[134:135], v[156:157], 1, v[130:131]
	v_cvt_pk_f16_f32 v130, v126, v127
	v_cvt_pk_f16_f32 v131, v128, v129
	v_cvt_pk_f16_f32 v132, v122, v123
	v_cvt_pk_f16_f32 v133, v124, v125
	global_store_dwordx4 v[134:135], v[130:133], off
	v_add_co_u32_e32 v136, vcc, s82, v134
	s_nop 0
	v_cvt_pk_f16_f32 v130, v118, v119
	v_cvt_pk_f16_f32 v131, v120, v121
	v_cvt_pk_f16_f32 v132, v114, v115
	v_cvt_pk_f16_f32 v133, v116, v117
	global_store_dwordx4 v[134:135], v[130:133], off offset:256
	v_addc_co_u32_e32 v137, vcc, 0, v135, vcc
	s_nop 0
	v_cvt_pk_f16_f32 v130, v78, v79
	v_cvt_pk_f16_f32 v131, v80, v81
	v_cvt_pk_f16_f32 v132, v74, v75
	v_cvt_pk_f16_f32 v133, v76, v77
	global_store_dwordx4 v[136:137], v[130:133], off
	s_mov_b32 s25, 0x90000
	s_nop 0
	v_cvt_pk_f16_f32 v130, v50, v51
	v_cvt_pk_f16_f32 v131, v52, v53
	v_cvt_pk_f16_f32 v132, v54, v55
	v_cvt_pk_f16_f32 v133, v56, v57
	global_store_dwordx4 v[136:137], v[130:133], off offset:256
	v_add_co_u32_e32 v136, vcc, s80, v134
	s_nop 0
	v_cvt_pk_f16_f32 v130, v26, v27
	v_cvt_pk_f16_f32 v131, v28, v29
	v_cvt_pk_f16_f32 v132, v30, v31
	v_cvt_pk_f16_f32 v133, v32, v33
	v_addc_co_u32_e32 v137, vcc, 0, v135, vcc
	global_store_dwordx4 v[136:137], v[130:133], off
	s_nop 1
	v_cvt_pk_f16_f32 v130, v18, v19
	v_cvt_pk_f16_f32 v131, v20, v21
	v_cvt_pk_f16_f32 v132, v22, v23
	v_cvt_pk_f16_f32 v133, v24, v25
	global_store_dwordx4 v[136:137], v[130:133], off offset:256
	v_add_co_u32_e32 v136, vcc, s38, v134
	s_nop 0
	v_cvt_pk_f16_f32 v130, v10, v11
	v_cvt_pk_f16_f32 v131, v12, v13
	v_cvt_pk_f16_f32 v132, v14, v15
	v_cvt_pk_f16_f32 v133, v16, v17
	v_addc_co_u32_e32 v137, vcc, 0, v135, vcc
	global_store_dwordx4 v[136:137], v[130:133], off
	s_nop 1
	v_cvt_pk_f16_f32 v130, v2, v3
	v_cvt_pk_f16_f32 v131, v4, v5
	v_cvt_pk_f16_f32 v132, v6, v7
	v_cvt_pk_f16_f32 v133, v8, v9
	global_store_dwordx4 v[136:137], v[130:133], off offset:256
	v_add_co_u32_e32 v136, vcc, s52, v134
	s_nop 0
	v_cvt_pk_f16_f32 v130, v106, v107
	v_cvt_pk_f16_f32 v131, v108, v109
	v_cvt_pk_f16_f32 v132, v110, v111
	v_cvt_pk_f16_f32 v133, v112, v113
	v_addc_co_u32_e32 v137, vcc, 0, v135, vcc
	global_store_dwordx4 v[136:137], v[130:133], off
	s_nop 1
	v_cvt_pk_f16_f32 v130, v98, v99
	v_cvt_pk_f16_f32 v131, v100, v101
	v_cvt_pk_f16_f32 v132, v102, v103
	v_cvt_pk_f16_f32 v133, v104, v105
	global_store_dwordx4 v[136:137], v[130:133], off offset:256
	v_add_co_u32_e32 v136, vcc, s25, v134
	s_nop 0
	v_cvt_pk_f16_f32 v130, v90, v91
	v_cvt_pk_f16_f32 v131, v92, v93
	v_cvt_pk_f16_f32 v132, v94, v95
	v_cvt_pk_f16_f32 v133, v96, v97
	v_addc_co_u32_e32 v137, vcc, 0, v135, vcc
	global_store_dwordx4 v[136:137], v[130:133], off
	s_mov_b32 s25, 0xa0000
	s_nop 0
	v_cvt_pk_f16_f32 v130, v82, v83
	v_cvt_pk_f16_f32 v131, v84, v85
	v_cvt_pk_f16_f32 v132, v86, v87
	v_cvt_pk_f16_f32 v133, v88, v89
	global_store_dwordx4 v[136:137], v[130:133], off offset:256
	v_add_co_u32_e32 v136, vcc, s25, v134
	s_nop 0
	v_cvt_pk_f16_f32 v130, v66, v67
	v_cvt_pk_f16_f32 v131, v68, v69
	v_cvt_pk_f16_f32 v132, v70, v71
	v_cvt_pk_f16_f32 v133, v72, v73
	v_addc_co_u32_e32 v137, vcc, 0, v135, vcc
	s_mov_b32 s25, 0xb0000
	global_store_dwordx4 v[136:137], v[130:133], off
	v_add_co_u32_e32 v134, vcc, s25, v134
	s_nop 0
	v_cvt_pk_f16_f32 v130, v58, v59
	v_cvt_pk_f16_f32 v131, v60, v61
	v_cvt_pk_f16_f32 v132, v62, v63
	v_cvt_pk_f16_f32 v133, v64, v65
	global_store_dwordx4 v[136:137], v[130:133], off offset:256
	v_addc_co_u32_e32 v135, vcc, 0, v135, vcc
	s_nop 0
	v_cvt_pk_f16_f32 v130, v42, v43
	v_cvt_pk_f16_f32 v131, v44, v45
	v_cvt_pk_f16_f32 v132, v46, v47
	v_cvt_pk_f16_f32 v133, v48, v49
	global_store_dwordx4 v[134:135], v[130:133], off
	s_nop 1
	v_cvt_pk_f16_f32 v130, v34, v35
	v_cvt_pk_f16_f32 v131, v36, v37
	v_cvt_pk_f16_f32 v132, v38, v39
	v_cvt_pk_f16_f32 v133, v40, v41
	global_store_dwordx4 v[134:135], v[130:133], off offset:256
	s_nop 1
	v_lshlrev_b64 v[130:131], 2, v[154:155]
	v_lshl_add_u64 v[132:133], s[14:15], 0, v[130:131]
	v_lshl_add_u64 v[130:131], s[0:1], 0, v[130:131]
	s_mov_b64 s[0:1], 0xe000
	v_add_co_u32_e32 v136, vcc, 0xe000, v130
	v_lshl_add_u64 v[134:135], v[130:131], 0, s[0:1]
	s_nop 0
	v_addc_co_u32_e32 v137, vcc, 0, v131, vcc
	s_mov_b64 s[0:1], 0xc000
	v_lshl_add_u64 v[188:189], v[130:131], 0, s[0:1]
	v_add_co_u32_e32 v130, vcc, 0xc000, v130
	global_load_dwordx4 v[150:153], v[132:133], off offset:16
	global_load_dwordx4 v[146:149], v[132:133], off
	v_addc_co_u32_e32 v131, vcc, 0, v131, vcc
	global_load_dwordx4 v[166:169], v[132:133], off offset:528
	global_load_dwordx4 v[162:165], v[132:133], off offset:512
	global_load_dwordx4 v[154:157], v[136:137], off
	global_load_dwordx4 v[174:177], v[134:135], off offset:528
	global_load_dwordx4 v[158:161], v[134:135], off offset:16
	global_load_dwordx4 v[170:173], v[134:135], off offset:512
	global_load_dwordx4 v[142:145], v[130:131], off
	s_nop 0
	global_load_dwordx4 v[130:133], v[188:189], off offset:528
	global_load_dwordx4 v[138:141], v[188:189], off offset:16
	global_load_dwordx4 v[134:137], v[188:189], off offset:512
	s_waitcnt lgkmcnt(0)
	s_barrier
	s_ashr_i32 s37, s36, 31
	s_and_saveexec_b64 s[0:1], s[8:9]
	s_cbranch_execz .LBB0_1274
	s_lshl_b64 s[8:9], s[36:37], 13
	s_add_u32 s8, s88, s8
	s_addc_u32 s9, s89, s9
	v_lshlrev_b64 v[188:189], 5, v[202:203]
	v_lshl_add_u64 v[188:189], s[8:9], 0, v[188:189]
	global_load_dword v190, v[188:189], off sc1
	global_load_dword v192, v[188:189], off offset:4 sc1
	global_load_dword v208, v[188:189], off offset:8 sc1
	global_load_dword v210, v[188:189], off offset:12 sc1
	global_load_dword v191, v[188:189], off offset:16 sc1
	global_load_dword v193, v[188:189], off offset:20 sc1
	global_load_dword v209, v[188:189], off offset:24 sc1
	global_load_dword v211, v[188:189], off offset:28 sc1
	s_waitcnt vmcnt(2)
	v_pk_add_f32 v[188:189], v[190:191], v[192:193]
	s_waitcnt vmcnt(0)
	v_pk_add_f32 v[190:191], v[208:209], v[210:211]
	s_nop 0
	v_pk_add_f32 v[188:189], v[188:189], v[190:191]
	s_nop 0
	v_add_f32_e32 v188, v188, v189
	v_fmamk_f32 v188, v188, 0x3a000000, v1
	v_rsq_f32_e32 v188, v188
	v_lshl_add_u32 v189, v202, 2, 0
	v_add_u32_e32 v189, 0x21540, v189
	ds_write_b32 v189, v188

;     __device__ __forceinline__ void operator()(f32x4 (&acc)[2][2][4][2], const Unit& u, int wr, int wc, int fr_, int fq_) const {
;     ...
;         if (wid == 0) { if (lane == 0) { unsigned sp = 0u; while (__hip_atomic_load(cnt + 16 * u.pm, __ATOMIC_RELAXED, __HIP_MEMORY_SCOPE_AGENT) < 64u) { __builtin_amdgcn_s_sleep(1); if (++sp > (1u << 17)) break; } } }
.LBB0_1509:
	s_or_b64 exec, exec, s[0:1]
	v_or_b32_e32 v188, s53, v201
	v_cmp_eq_u32_e32 vcc, 0, v188
	s_and_saveexec_b64 s[0:1], vcc
	s_cbranch_execz .LBB0_1516
	s_lshl_b32 s60, s34, 4
	s_ashr_i32 s61, s60, 31
	s_lshl_b64 s[60:61], s[60:61], 2
	s_add_u32 s60, s4, s60
	s_addc_u32 s61, s5, s61
	s_mov_b32 s31, 0x20001
	s_branch .LBB0_1512
.LBB0_1511:
	s_and_b64 vcc, exec, s[44:45]
	s_cbranch_vccnz .LBB0_1516
.LBB0_1512:
	global_load_dword v188, v187, s[60:61] sc1
	s_mov_b64 s[44:45], -1
	s_waitcnt vmcnt(0)
	v_cmp_lt_u32_e32 vcc, 63, v188
	s_cbranch_vccnz .LBB0_1511
	s_sleep 1
	global_load_dword v188, v187, s[60:61] sc1
	s_waitcnt vmcnt(0)
	v_cmp_gt_u32_e32 vcc, 64, v188
	s_cbranch_vccz .LBB0_1511
	s_sleep 1
	global_load_dword v188, v187, s[60:61] sc1
	s_waitcnt vmcnt(0)
	v_cmp_gt_u32_e32 vcc, 64, v188
	s_cbranch_vccz .LBB0_1511
	s_add_i32 s31, s31, -3
	s_cmp_eq_u32 s31, 0
	s_cselect_b64 s[44:45], -1, 0
	s_sleep 1
	s_branch .LBB0_1511
; __device__ __forceinline__ u32x4 pack8h(const f32x4 v0, const f32x4 v1) { u32x4 w; w.x = pk_h2(v0[0], v0[1]); w.y = pk_h2(v0[2], v0[3]); w.z = pk_h2(v1[0], v1[1]); w.w = pk_h2(v1[2], v1[3]); return w; }
;     __device__ __forceinline__ void operator()(f32x4 (&acc)[2][2][4][2], const Unit& u, int wr, int wc, int fr_, int fq_) const {
;     ...
;         if (!FINAL) { bf16_t* out = (lat ? out_lat : out_ctx) + roff;
; #pragma unroll
;             for (int ai = 0; ai < 2; ++ai)
; #pragma unroll
;                 for (int m = 0; m < 4; ++m)
; #pragma unroll
;                     for (int bj = 0; bj < 2; ++bj) *(u32x4*)(out + (size_t)(ai * HALF + m * 16) * DM + bj * HALF) = pack8h(acc[ai][bj][m][0], acc[ai][bj][m][1]); }
;         f32x4 av[2][2], sv[2][2];
; #pragma unroll
;         for (int bj = 0; bj < 2; ++bj)
; #pragma unroll
;             for (int n = 0; n < 2; ++n) { const int col = col0 + bj * HALF + 4 * n; const f32x4 g = *(const f32x4*)(gain + col);
;                 if (FINAL) { av[bj][n] = g; sv[bj][n] = (f32x4){0.f, 0.f, 0.f, 0.f}; }
;                 else { const float* mp = nmod + (size_t)rb * NMODC; av[bj][n] = g * (*(const f32x4*)(mp + isc * DM + col) + 1.0f); sv[bj][n] = *(const f32x4*)(mp + ish * DM + col); } }
;         if (wid == 0) { if (lane == 0) { unsigned sp = 0u; while (__hip_atomic_load(cnt + 16 * u.pm, __ATOMIC_RELAXED, __HIP_MEMORY_SCOPE_AGENT) < 64u) { __builtin_amdgcn_s_sleep(1); if (++sp > (1u << 17)) break; } } }
;         asm volatile("s_waitcnt lgkmcnt(0)" ::: "memory"); __builtin_amdgcn_s_barrier(); asm volatile("" ::: "memory");
;         if (lane < 32) { const float* slot = xbuf + ((size_t)u.pm * BM + row) * 8; float t8[8];
; #pragma unroll
;             for (int t = 0; t < 8; ++t) t8[t] = __hip_atomic_load(slot + t, __ATOMIC_RELAXED, __HIP_MEMORY_SCOPE_AGENT);
;             const float tot = ((t8[0] + t8[1]) + (t8[2] + t8[3])) + ((t8[4] + t8[5]) + (t8[6] + t8[7]));
;             S[row] = __builtin_amdgcn_rsqf(tot * (1.0f / DM) + 1e-6f); }
.LBB0_1516:
	s_or_b64 exec, exec, s[0:1]
	s_and_b64 s[0:1], s[40:41], exec
	s_cselect_b32 s0, s13, s15
	s_cselect_b32 s1, s12, s14
	v_mov_b32_e32 v130, s1
	v_mov_b32_e32 v131, s0
	v_lshl_add_u64 v[134:135], v[148:149], 1, v[130:131]
	v_cvt_pk_f16_f32 v130, v30, v31
	v_cvt_pk_f16_f32 v131, v32, v33
	v_cvt_pk_f16_f32 v132, v22, v23
	v_cvt_pk_f16_f32 v133, v24, v25
	global_store_dwordx4 v[134:135], v[130:133], off
	v_add_co_u32_e32 v136, vcc, s80, v134
	s_nop 0
	v_cvt_pk_f16_f32 v130, v26, v27
	v_cvt_pk_f16_f32 v131, v28, v29
	v_cvt_pk_f16_f32 v132, v14, v15
	v_cvt_pk_f16_f32 v133, v16, v17
	global_store_dwordx4 v[134:135], v[130:133], off offset:256
	v_addc_co_u32_e32 v137, vcc, 0, v135, vcc
	s_nop 0
	v_cvt_pk_f16_f32 v130, v18, v19
	v_cvt_pk_f16_f32 v131, v20, v21
	v_cvt_pk_f16_f32 v132, v10, v11
	v_cvt_pk_f16_f32 v133, v12, v13
	global_store_dwordx4 v[136:137], v[130:133], off
	s_mov_b32 s0, 0x90000
	v_cvt_pk_f16_f32 v130, v42, v43
	v_cvt_pk_f16_f32 v131, v44, v45
	v_cvt_pk_f16_f32 v132, v46, v47
	v_cvt_pk_f16_f32 v133, v48, v49
	global_store_dwordx4 v[136:137], v[130:133], off offset:256
	v_add_co_u32_e32 v136, vcc, s75, v134
	s_nop 0
	v_cvt_pk_f16_f32 v130, v50, v51
	v_cvt_pk_f16_f32 v131, v52, v53
	v_cvt_pk_f16_f32 v132, v54, v55
	v_cvt_pk_f16_f32 v133, v56, v57
	v_addc_co_u32_e32 v137, vcc, 0, v135, vcc
	global_store_dwordx4 v[136:137], v[130:133], off
	s_nop 1
	v_cvt_pk_f16_f32 v130, v66, v67
	v_cvt_pk_f16_f32 v131, v68, v69
	v_cvt_pk_f16_f32 v132, v70, v71
	v_cvt_pk_f16_f32 v133, v72, v73
	global_store_dwordx4 v[136:137], v[130:133], off offset:256
	v_add_co_u32_e32 v136, vcc, s82, v134
	s_nop 0
	v_cvt_pk_f16_f32 v130, v74, v75
	v_cvt_pk_f16_f32 v131, v76, v77
	v_cvt_pk_f16_f32 v132, v78, v79
	v_cvt_pk_f16_f32 v133, v80, v81
	v_addc_co_u32_e32 v137, vcc, 0, v135, vcc
	global_store_dwordx4 v[136:137], v[130:133], off
	s_nop 1
	v_cvt_pk_f16_f32 v130, v82, v83
	v_cvt_pk_f16_f32 v131, v84, v85
	v_cvt_pk_f16_f32 v132, v86, v87
	v_cvt_pk_f16_f32 v133, v88, v89
	global_store_dwordx4 v[136:137], v[130:133], off offset:256
	v_add_co_u32_e32 v136, vcc, s52, v134
	s_nop 0
	v_cvt_pk_f16_f32 v130, v106, v107
	v_cvt_pk_f16_f32 v131, v108, v109
	v_cvt_pk_f16_f32 v132, v110, v111
	v_cvt_pk_f16_f32 v133, v112, v113
	v_addc_co_u32_e32 v137, vcc, 0, v135, vcc
	global_store_dwordx4 v[136:137], v[130:133], off
	s_nop 1
	v_cvt_pk_f16_f32 v130, v114, v115
	v_cvt_pk_f16_f32 v131, v116, v117
	v_cvt_pk_f16_f32 v132, v118, v119
	v_cvt_pk_f16_f32 v133, v120, v121
	global_store_dwordx4 v[136:137], v[130:133], off offset:256
	v_add_co_u32_e32 v136, vcc, s0, v134
	s_nop 0
	v_cvt_pk_f16_f32 v130, v122, v123
	v_cvt_pk_f16_f32 v131, v124, v125
	v_cvt_pk_f16_f32 v132, v126, v127
	v_cvt_pk_f16_f32 v133, v128, v129
	v_addc_co_u32_e32 v137, vcc, 0, v135, vcc
	global_store_dwordx4 v[136:137], v[130:133], off
	s_mov_b32 s0, 0xa0000
	s_nop 0
	v_cvt_pk_f16_f32 v130, v102, v103
	v_cvt_pk_f16_f32 v131, v104, v105
	v_cvt_pk_f16_f32 v132, v98, v99
	v_cvt_pk_f16_f32 v133, v100, v101
	global_store_dwordx4 v[136:137], v[130:133], off offset:256
	v_add_co_u32_e32 v136, vcc, s0, v134
	s_nop 0
	v_cvt_pk_f16_f32 v130, v94, v95
	v_cvt_pk_f16_f32 v131, v96, v97
	v_cvt_pk_f16_f32 v132, v90, v91
	v_cvt_pk_f16_f32 v133, v92, v93
	v_addc_co_u32_e32 v137, vcc, 0, v135, vcc
	s_mov_b32 s0, 0xb0000
	global_store_dwordx4 v[136:137], v[130:133], off
	v_add_co_u32_e32 v134, vcc, s0, v134
	s_nop 0
	v_cvt_pk_f16_f32 v130, v62, v63
	v_cvt_pk_f16_f32 v131, v64, v65
	v_cvt_pk_f16_f32 v132, v58, v59
	v_cvt_pk_f16_f32 v133, v60, v61
	global_store_dwordx4 v[136:137], v[130:133], off offset:256
	v_addc_co_u32_e32 v135, vcc, 0, v135, vcc
	s_nop 0
	v_cvt_pk_f16_f32 v130, v38, v39
	v_cvt_pk_f16_f32 v131, v40, v41
	v_cvt_pk_f16_f32 v132, v34, v35
	v_cvt_pk_f16_f32 v133, v36, v37
	global_store_dwordx4 v[134:135], v[130:133], off
	s_add_u32 s0, s92, s36
	s_addc_u32 s1, s93, s37
	v_cvt_pk_f16_f32 v130, v6, v7
	v_cvt_pk_f16_f32 v131, v8, v9
	v_cvt_pk_f16_f32 v132, v2, v3
	v_cvt_pk_f16_f32 v133, v4, v5
	global_store_dwordx4 v[134:135], v[130:133], off offset:256
	s_nop 1
	v_lshlrev_b64 v[130:131], 2, v[146:147]
	v_lshl_add_u64 v[134:135], s[0:1], 0, v[130:131]
	s_mov_b64 s[0:1], 0x2000
	v_add_co_u32_e32 v136, vcc, s85, v134
	v_lshl_add_u64 v[132:133], s[18:19], 0, v[130:131]
	v_lshl_add_u64 v[130:131], v[134:135], 0, s[0:1]
	v_addc_co_u32_e32 v137, vcc, 0, v135, vcc
	global_load_dwordx4 v[150:153], v[132:133], off offset:16
	global_load_dwordx4 v[146:149], v[132:133], off
	global_load_dwordx4 v[138:141], v[134:135], off offset:16
	global_load_dwordx4 v[142:145], v[134:135], off
	global_load_dwordx4 v[166:169], v[132:133], off offset:528
	global_load_dwordx4 v[162:165], v[132:133], off offset:512
	global_load_dwordx4 v[154:157], v[136:137], off
	global_load_dwordx4 v[174:177], v[130:131], off offset:528
	global_load_dwordx4 v[158:161], v[130:131], off offset:16
	global_load_dwordx4 v[170:173], v[130:131], off offset:512
	s_nop 0
	global_load_dwordx4 v[130:133], v[134:135], off offset:528
	s_nop 0
	global_load_dwordx4 v[134:137], v[134:135], off offset:512
	s_waitcnt lgkmcnt(0)
	s_barrier
	s_ashr_i32 s35, s34, 31
	s_and_saveexec_b64 s[0:1], s[8:9]
	s_cbranch_execz .LBB0_1518
	s_lshl_b64 s[8:9], s[34:35], 13
	s_add_u32 s8, s96, s8
	s_addc_u32 s9, s97, s9
	v_lshlrev_b64 v[188:189], 5, v[202:203]
	v_lshl_add_u64 v[188:189], s[8:9], 0, v[188:189]
	global_load_dword v190, v[188:189], off sc1
	global_load_dword v192, v[188:189], off offset:4 sc1
	global_load_dword v208, v[188:189], off offset:8 sc1
	global_load_dword v210, v[188:189], off offset:12 sc1
	global_load_dword v191, v[188:189], off offset:16 sc1
	global_load_dword v193, v[188:189], off offset:20 sc1
	global_load_dword v209, v[188:189], off offset:24 sc1
	global_load_dword v211, v[188:189], off offset:28 sc1
	s_waitcnt vmcnt(2)
	v_pk_add_f32 v[188:189], v[190:191], v[192:193]
	s_waitcnt vmcnt(0)
	v_pk_add_f32 v[190:191], v[208:209], v[210:211]
	s_nop 0
	v_pk_add_f32 v[188:189], v[188:189], v[190:191]
	s_nop 0
	v_add_f32_e32 v188, v188, v189
	v_fmamk_f32 v188, v188, 0x3a000000, v1
	v_rsq_f32_e32 v188, v188
	v_lshl_add_u32 v189, v202, 2, 0
	v_add_u32_e32 v189, 0x21540, v189
	ds_write_b32 v189, v188
